# nt hints + left-over projection units beside the up-projection phase + MLA context units on workgroups 32..63
# speedup vs baseline: 1.0214x; 1.0016x over previous
.LBB0_835:
	s_bitcmp1_b32 s90, 1
	s_mov_b32 s34, 0
	s_cbranch_scc1 .LBB0_884
	s_add_u32 s35, s92, 0x32f00000
	s_addc_u32 s38, s93, 0
	s_add_u32 s39, s92, 0x39200000
	s_addc_u32 s47, s93, 0
	s_add_u32 s48, s92, 0x400000
	s_addc_u32 s49, s93, 0
	s_lshl_b32 s50, s50, 8
	s_add_i32 s4, s2, 0xffffffe0
	s_cmp_lt_u32 s4, 32
	s_cselect_b64 s[10:11], -1, 0
	s_and_b32 s51, s4, 15
	s_lshr_b32 s4, s4, 4
	s_mul_i32 s52, s4, 0x2100
	s_addk_i32 s52, 0x2000
	v_mov_b32_e32 v165, 0
	s_mov_b32 s53, 0x2aaaaaab
	s_movk_i32 s54, 0xffe8
	s_movk_i32 s55, 0x70
	s_mov_b32 s56, 0x42ddb3d8
	s_mov_b64 s[12:13], 0x39300100
	s_mov_b64 s[14:15], 0x39340100
	s_mov_b64 s[16:17], 0xc0000
	s_mov_b64 s[18:19], 0x140000
	s_mov_b64 s[22:23], 0x100000
	s_movk_i32 s57, 0x1000
	s_mov_b32 s58, 0x9000
	s_mov_b32 s59, 0x11000
	s_mov_b32 s60, 0x19000
	s_movk_i32 s61, 0x110
	s_mov_b32 s62, 0x21000
	s_mov_b32 s63, 0x29000
	s_mov_b32 s64, 0x31000
	s_mov_b32 s65, 0x39000
	v_mov_b32_e32 v1, 0xf149f2ca
	s_branch .LBB0_839
